# P4: wave owns 64 contiguous cols (remap) + permlane merge + lane-pair exchange -> h1 tile stored as full 128B lines
# speedup vs baseline: 1.0069x; 1.0069x over previous
.LBB0_369:
	s_load_dwordx2 s[16:17], s[0:1], 0x0
	s_andn2_b64 vcc, exec, s[6:7]
	s_cbranch_vccnz .LBB0_407
	v_lshlrev_b32_e32 v0, 4, v168
	v_and_b32_e32 v1, 32, v168
	v_bfe_u32 v118, v168, 2, 4
	v_lshrrev_b32_e32 v2, 3, v168
	s_movk_i32 s7, 0x70
	v_add_u32_e32 v119, 0x2000, v0
	s_add_u32 s3, s30, 0x3a00000
	v_bitop3_b32 v116, v0, v1, 48 bitop3:0x6c
	v_and_or_b32 v2, v2, s7, v118
	v_lshrrev_b32_e32 v0, 7, v119
	s_movk_i32 s7, 0xf0
	s_addc_u32 s4, s31, 0
	s_lshr_b32 s6, s10, 6
	v_and_or_b32 v0, v0, s7, v118
	s_lshr_b32 s7, s10, 8
	v_and_b32_e32 v117, 64, v168
	s_lshl_b32 s45, s6, 10
	s_lshl_b32 s6, s7, 6
	s_lshl_b32 s9, s56, 8
	s_bfe_u32 s5, s10, 0x20006
	v_or_b32_e32 v1, v116, v117
	v_and_b32_e32 v122, 15, v168
	s_add_i32 s9, s9, s6
	v_lshl_or_b32 v166, v0, 11, v1
	v_bfe_u32 v120, v168, 4, 2
	s_lshl_b32 s8, s5, 6
	v_or_b32_e32 v0, s9, v122
	s_lshl_b32 s9, s36, 8
	s_or_b32 s9, s9, s8
	v_lshlrev_b32_e32 v121, 2, v120
	v_lshl_or_b32 v164, v2, 11, v1
	v_or_b32_e32 v2, s9, v121
	v_ashrrev_i32_e32 v1, 31, v0
	v_ashrrev_i32_e32 v3, 31, v2
	v_lshlrev_b64 v[4:5], 13, v[0:1]
	s_waitcnt lgkmcnt(0)
	v_lshl_add_u64 v[4:5], s[16:17], 0, v[4:5]
	v_lshlrev_b64 v[2:3], 2, v[2:3]
	v_lshl_add_u64 v[100:101], v[4:5], 0, v[2:3]
	v_or_b32_e32 v4, 16, v0
	v_ashrrev_i32_e32 v5, 31, v4
	v_lshlrev_b64 v[4:5], 13, v[4:5]
	v_lshl_add_u64 v[4:5], s[16:17], 0, v[4:5]
	s_mov_b32 s47, 0x100000
	v_lshl_add_u64 v[4:5], v[4:5], 0, v[2:3]
	v_add_co_u32_e32 v10, vcc, s47, v100
	global_load_dwordx4 v[72:75], v[100:101], off nt
	global_load_dwordx4 v[68:71], v[100:101], off offset:64 nt
	global_load_dwordx4 v[20:23], v[100:101], off offset:128 nt
	global_load_dwordx4 v[16:19], v[100:101], off offset:192 nt
	global_load_dwordx4 v[88:91], v[4:5], off nt
	global_load_dwordx4 v[76:79], v[4:5], off offset:64 nt
	global_load_dwordx4 v[36:39], v[4:5], off offset:128 nt
	global_load_dwordx4 v[32:35], v[4:5], off offset:192 nt
	v_or_b32_e32 v4, 32, v0
	v_or_b32_e32 v0, 48, v0
	v_addc_co_u32_e32 v11, vcc, 0, v101, vcc
	s_mov_b32 s65, 0x120000
	v_ashrrev_i32_e32 v5, 31, v4
	v_ashrrev_i32_e32 v1, 31, v0
	v_add_co_u32_e32 v26, vcc, s65, v100
	v_lshlrev_b64 v[4:5], 13, v[4:5]
	v_lshlrev_b64 v[0:1], 13, v[0:1]
	v_addc_co_u32_e32 v27, vcc, 0, v101, vcc
	s_mov_b32 s66, 0x140000
	v_lshl_add_u64 v[4:5], s[16:17], 0, v[4:5]
	v_lshl_add_u64 v[0:1], s[16:17], 0, v[0:1]
	s_mov_b64 s[18:19], 0x100000
	s_mov_b64 s[20:21], 0x120000
	s_mov_b64 s[26:27], 0x140000
	v_add_co_u32_e32 v112, vcc, s66, v100
	v_lshl_add_u64 v[4:5], v[4:5], 0, v[2:3]
	v_lshl_add_u64 v[0:1], v[0:1], 0, v[2:3]
	v_lshl_add_u64 v[8:9], v[100:101], 0, s[18:19]
	v_lshl_add_u64 v[24:25], v[100:101], 0, s[20:21]
	v_lshl_add_u64 v[102:103], v[100:101], 0, s[26:27]
	v_addc_co_u32_e32 v113, vcc, 0, v101, vcc
	s_mov_b64 s[28:29], 0x160000
	s_mov_b32 s9, 0x160000
	s_ashr_i32 s57, s56, 31
	s_ashr_i32 s37, s36, 31
	global_load_dwordx4 v[96:99], v[4:5], off nt
	global_load_dwordx4 v[92:95], v[4:5], off offset:64 nt
	global_load_dwordx4 v[44:47], v[4:5], off offset:128 nt
	global_load_dwordx4 v[40:43], v[4:5], off offset:192 nt
	global_load_dwordx4 v[108:111], v[0:1], off nt
	global_load_dwordx4 v[104:107], v[0:1], off offset:64 nt
	global_load_dwordx4 v[56:59], v[0:1], off offset:128 nt
	global_load_dwordx4 v[48:51], v[0:1], off offset:192 nt
	global_load_dwordx4 v[52:55], v[8:9], off offset:64 nt
	global_load_dwordx4 v[4:7], v[8:9], off offset:128 nt
	global_load_dwordx4 v[64:67], v[10:11], off nt
	s_nop 0
	global_load_dwordx4 v[0:3], v[8:9], off offset:192 nt
	global_load_dwordx4 v[60:63], v[24:25], off offset:64 nt
	global_load_dwordx4 v[12:15], v[24:25], off offset:128 nt
	global_load_dwordx4 v[84:87], v[26:27], off nt
	s_nop 0
	global_load_dwordx4 v[8:11], v[24:25], off offset:192 nt
	global_load_dwordx4 v[80:83], v[102:103], off offset:64 nt
	global_load_dwordx4 v[28:31], v[102:103], off offset:128 nt
	global_load_dwordx4 v[156:159], v[112:113], off nt
	s_nop 0
	global_load_dwordx4 v[24:27], v[102:103], off offset:192 nt
	v_lshl_add_u64 v[102:103], v[100:101], 0, s[28:29]
	v_add_co_u32_e32 v100, vcc, s9, v100
	s_lshl_b64 s[38:39], s[56:57], 19
	s_ashr_i32 s9, s56, 3
	s_lshl_b64 s[40:41], s[36:37], 19
	s_add_u32 s58, s3, s40
	s_addc_u32 s59, s4, s41
	s_add_i32 s67, s45, 0x10000
	s_add_i32 s68, s45, 0x12000
	s_add_u32 s37, s22, s38
	s_addc_u32 s40, s23, s39
	s_mov_b32 m0, s67
	s_add_u32 s38, s58, 0x40000
	v_addc_co_u32_e32 v101, vcc, 0, v101, vcc
	global_load_dwordx4 v[152:155], v[102:103], off offset:64 nt
	global_load_dwordx4 v[148:151], v[102:103], off offset:128 nt
	global_load_dwordx4 v[160:163], v[100:101], off nt
	global_load_dwordx4 v[144:147], v[102:103], off offset:192 nt
	s_mul_hi_i32 s11, s9, 0x2400000
	s_mul_i32 s9, s9, 0x2400000
	global_load_lds_dwordx4 v164, s[58:59]
	s_mov_b32 m0, s68
	s_addc_u32 s39, s59, 0
	s_add_i32 s69, s45, 0x14000
	s_add_i32 s70, s45, 0x16000
	global_load_lds_dwordx4 v166, s[58:59]
	s_mov_b32 m0, s69
	s_add_u32 s60, s37, s9
	global_load_lds_dwordx4 v164, s[38:39]
	s_mov_b32 m0, s70
	s_addc_u32 s61, s40, s11
	s_add_i32 s71, s45, 0x2000
	global_load_lds_dwordx4 v166, s[38:39]
	s_mov_b32 m0, s45
	s_add_u32 s38, s60, 0x40000
	global_load_lds_dwordx4 v164, s[60:61]
	s_mov_b32 m0, s71
	s_addc_u32 s39, s61, 0
	s_add_i32 s72, s45, 0x4000
	global_load_lds_dwordx4 v166, s[60:61]
	s_mov_b32 m0, s72
	s_add_i32 s73, s45, 0x6000
	global_load_lds_dwordx4 v164, s[38:39]
	s_mov_b32 m0, s73
	v_mov_b32_e32 v165, 0
	global_load_lds_dwordx4 v166, s[38:39]
	v_mov_b32_e32 v167, v165
	s_cmp_eq_u32 s7, 1
	s_mov_b32 s37, 0
	v_lshl_add_u64 v[114:115], s[58:59], 0, v[164:165]
	v_lshl_add_u64 v[112:113], s[58:59], 0, v[166:167]
	v_lshl_add_u64 v[100:101], s[60:61], 0, v[164:165]
	s_cselect_b64 s[38:39], -1, 0
	s_cmp_lg_u32 s7, 1
	v_lshl_add_u64 v[102:103], s[60:61], 0, v[166:167]
	s_cbranch_scc1 .LBB0_372
	s_barrier
.LBB0_372:
	s_add_i32 s74, s45, 0x18000
	s_mov_b64 s[40:41], 0x80
	v_lshl_add_u64 v[114:115], v[114:115], 0, s[40:41]
	s_mov_b32 m0, s74
	s_add_i32 s75, s45, 0x1a000
	s_lshl_b32 s7, s7, 13
	s_lshl_b32 s9, s5, 13
	s_waitcnt vmcnt(2)
	s_barrier
	global_load_lds_dwordx4 v[114:115], off
	v_lshl_add_u64 v[112:113], v[112:113], 0, s[40:41]
	s_mov_b32 m0, s75
	s_add_i32 s76, s45, 0x8000
	s_add_i32 s77, s45, 0xa000
	global_load_lds_dwordx4 v[112:113], off
	v_lshl_add_u64 v[100:101], v[100:101], 0, s[40:41]
	s_mov_b32 m0, s76
	s_add_u32 s42, s58, 0x40080
	global_load_lds_dwordx4 v[100:101], off
	v_lshl_add_u64 v[100:101], v[102:103], 0, s[40:41]
	s_mov_b32 m0, s77
	s_addc_u32 s43, s59, 0
	s_add_i32 s78, s45, 0x1c000
	global_load_lds_dwordx4 v[100:101], off
	v_lshl_add_u64 v[100:101], s[42:43], 0, v[164:165]
	s_mov_b32 m0, s78
	s_add_i32 s79, s45, 0x1e000
	global_load_lds_dwordx4 v[100:101], off
	v_lshl_add_u64 v[100:101], s[42:43], 0, v[166:167]
	s_mov_b32 m0, s79
	v_or_b32_e32 v169, s6, v122
	global_load_lds_dwordx4 v[100:101], off
	v_lshlrev_b32_e32 v100, 4, v120
	v_lshlrev_b32_e32 v101, 6, v169
	s_movk_i32 s6, 0x3c0
	v_lshlrev_b32_e32 v102, 2, v169
	v_and_or_b32 v101, v101, s6, v100
	v_and_b32_e32 v102, 32, v102
	v_bitop3_b32 v178, v101, s7, v102 bitop3:0xde
	v_lshlrev_b32_e32 v101, 6, v168
	v_and_or_b32 v100, v101, s6, v100
	v_lshlrev_b32_e32 v101, 2, v168
	v_and_b32_e32 v101, 32, v101
	v_bitop3_b32 v179, s9, v100, v101 bitop3:0xf6
	v_lshlrev_b32_e32 v100, 8, v168
	v_and_b32_e32 v100, 0x38000, v100
	v_lshlrev_b32_e32 v101, 11, v118
	v_or3_b32 v100, v116, v100, v101
	v_add_u32_e32 v170, v100, v117
	v_lshlrev_b32_e32 v100, 4, v119
	v_and_b32_e32 v100, 0x78000, v100
	s_waitcnt vmcnt(6)
	v_or3_b32 v100, v116, v100, v101
	s_cmpk_lt_u32 s10, 0x100
	v_add_u32_e32 v172, v100, v117
	v_mbcnt_lo_u32_b32 v100, -1, 0
	s_cselect_b64 s[42:43], -1, 0
	v_cmp_eq_u32_e64 s[6:7], 0, v120
	s_ashr_i32 s80, s33, 31
	s_ashr_i32 s81, s2, 31
	v_or_b32_e32 v180, s8, v121
	v_mov_b32_e32 v171, v165
	v_mov_b32_e32 v173, v165
	v_mov_b64_e32 v[174:175], 0x200
	v_mov_b64_e32 v[176:177], 0x1ff
	s_mov_b32 s44, 0x44800000
	s_add_i32 s82, s45, 0xc000
	s_add_i32 s83, s45, 0xe000
	v_mov_b32_e32 v181, 0x7f
	v_mbcnt_hi_u32_b32 v182, -1, v100
	s_mov_b32 s46, 0x3a800000
	s_mov_b32 s84, 0
	s_barrier
	s_branch .LBB0_375

.LBB0_384:
	v_or_b32_e32 v0, 0x10000, v179
	v_add_u32_e32 v4, 0x10400, v179
	v_add_u32_e32 v8, 0x10800, v179
	v_add_u32_e32 v12, 0x10c00, v179
	v_or_b32_e32 v144, 0x11000, v179
	ds_read_b128 v[0:3], v0
	ds_read_b128 v[4:7], v4
	ds_read_b128 v[8:11], v8
	ds_read_b128 v[12:15], v12
	v_add_u32_e32 v145, 0x11400, v179
	ds_read_b128 v[152:155], v144
	ds_read_b128 v[156:159], v145
	v_add_u32_e32 v144, 0x11800, v179
	v_add_u32_e32 v145, 0x11c00, v179
	ds_read_b128 v[184:187], v144
	ds_read_b128 v[188:191], v145
	s_add_u32 s58, s10, 0xfffc0080
	s_addc_u32 s59, s11, -1
	s_cmp_eq_u32 s86, 12
	s_cselect_b32 s61, s53, s59
	s_cselect_b32 s60, s52, s58
	s_cselect_b32 s59, s49, s85
	s_cselect_b32 s58, s51, s57
	s_mov_b32 m0, s82
	v_lshl_add_u64 v[160:161], s[10:11], 0, v[170:171]
	ds_read_b128 v[144:147], v178
	ds_read_b128 v[148:151], v178 offset:1024
	ds_read_b128 v[192:195], v178 offset:2048
	ds_read_b128 v[196:199], v178 offset:3072
	ds_read_b128 v[200:203], v178 offset:4096
	ds_read_b128 v[204:207], v178 offset:5120
	ds_read_b128 v[208:211], v178 offset:6144
	ds_read_b128 v[212:215], v178 offset:7168
	global_load_lds_dwordx4 v[160:161], off
	v_lshl_add_u64 v[160:161], s[10:11], 0, v[172:173]
	s_mov_b32 m0, s83
	s_nop 0
	global_load_lds_dwordx4 v[160:161], off
	s_waitcnt vmcnt(8)
	s_waitcnt lgkmcnt(0)
	s_barrier
	s_setprio 1
	s_waitcnt lgkmcnt(0)
	v_mfma_scale_f32_16x16x128_f8f6f4 v[132:135], v[0:7], v[144:151], v[132:135], v181, v181 op_sel_hi:[0,0,0]
	v_mfma_scale_f32_16x16x128_f8f6f4 v[128:131], v[8:15], v[144:151], v[128:131], v181, v181 op_sel_hi:[0,0,0]
	v_mfma_scale_f32_16x16x128_f8f6f4 v[116:119], v[0:7], v[192:199], v[116:119], v181, v181 op_sel_hi:[0,0,0]
	v_mfma_scale_f32_16x16x128_f8f6f4 v[112:115], v[8:15], v[192:199], v[112:115], v181, v181 op_sel_hi:[0,0,0]
	v_mfma_scale_f32_16x16x128_f8f6f4 v[100:103], v[0:7], v[200:207], v[100:103], v181, v181 op_sel_hi:[0,0,0]
	v_mfma_scale_f32_16x16x128_f8f6f4 v[96:99], v[8:15], v[200:207], v[96:99], v181, v181 op_sel_hi:[0,0,0]
	v_mfma_scale_f32_16x16x128_f8f6f4 v[76:79], v[0:7], v[208:215], v[76:79], v181, v181 op_sel_hi:[0,0,0]
	v_mfma_scale_f32_16x16x128_f8f6f4 v[72:75], v[8:15], v[208:215], v[72:75], v181, v181 op_sel_hi:[0,0,0]
	s_setprio 0
	s_setprio 1
	v_mfma_scale_f32_16x16x128_f8f6f4 v[140:143], v[152:159], v[144:151], v[140:143], v181, v181 op_sel_hi:[0,0,0]
	v_mfma_scale_f32_16x16x128_f8f6f4 v[136:139], v[184:191], v[144:151], v[136:139], v181, v181 op_sel_hi:[0,0,0]
	v_mfma_scale_f32_16x16x128_f8f6f4 v[124:127], v[152:159], v[192:199], v[124:127], v181, v181 op_sel_hi:[0,0,0]
	v_mfma_scale_f32_16x16x128_f8f6f4 v[120:123], v[184:191], v[192:199], v[120:123], v181, v181 op_sel_hi:[0,0,0]
	v_mfma_scale_f32_16x16x128_f8f6f4 v[108:111], v[152:159], v[200:207], v[108:111], v181, v181 op_sel_hi:[0,0,0]
	v_mfma_scale_f32_16x16x128_f8f6f4 v[104:107], v[184:191], v[200:207], v[104:107], v181, v181 op_sel_hi:[0,0,0]
	v_mfma_scale_f32_16x16x128_f8f6f4 v[92:95], v[152:159], v[208:215], v[92:95], v181, v181 op_sel_hi:[0,0,0]
	v_mfma_scale_f32_16x16x128_f8f6f4 v[88:91], v[184:191], v[208:215], v[88:91], v181, v181 op_sel_hi:[0,0,0]
	s_setprio 0
	s_barrier
	s_mov_b32 m0, s67
	v_lshl_add_u64 v[144:145], s[58:59], 0, v[164:165]
	s_add_u32 s88, s58, 0x40000
	ds_read_b128 v[192:195], v178 offset:16384
	ds_read_b128 v[196:199], v178 offset:17408
	ds_read_b128 v[200:203], v178 offset:18432
	ds_read_b128 v[204:207], v178 offset:19456
	ds_read_b128 v[208:211], v178 offset:20480
	ds_read_b128 v[212:215], v178 offset:21504
	ds_read_b128 v[216:219], v178 offset:22528
	ds_read_b128 v[220:223], v178 offset:23552
	global_load_lds_dwordx4 v[144:145], off
	v_lshl_add_u64 v[146:147], s[58:59], 0, v[166:167]
	s_mov_b32 m0, s68
	s_addc_u32 s89, s59, 0
	global_load_lds_dwordx4 v[146:147], off
	v_lshl_add_u64 v[148:149], s[88:89], 0, v[164:165]
	s_mov_b32 m0, s69
	v_lshl_add_u64 v[150:151], s[60:61], 0, v[166:167]
	global_load_lds_dwordx4 v[148:149], off
	v_lshl_add_u64 v[148:149], s[88:89], 0, v[166:167]
	s_mov_b32 m0, s70
	s_nop 0
	global_load_lds_dwordx4 v[148:149], off
	v_lshl_add_u64 v[148:149], s[60:61], 0, v[164:165]
	s_mov_b32 m0, s45
	s_nop 0
	global_load_lds_dwordx4 v[148:149], off
	s_mov_b32 m0, s71
	s_nop 0
	global_load_lds_dwordx4 v[150:151], off
	s_waitcnt vmcnt(8)
	s_waitcnt lgkmcnt(0)
	s_barrier
	s_setprio 1
	s_waitcnt lgkmcnt(0)
	v_mfma_scale_f32_16x16x128_f8f6f4 v[68:71], v[0:7], v[192:199], v[68:71], v181, v181 op_sel_hi:[0,0,0]
	v_mfma_scale_f32_16x16x128_f8f6f4 v[64:67], v[8:15], v[192:199], v[64:67], v181, v181 op_sel_hi:[0,0,0]
	v_mfma_scale_f32_16x16x128_f8f6f4 v[52:55], v[0:7], v[200:207], v[52:55], v181, v181 op_sel_hi:[0,0,0]
	v_mfma_scale_f32_16x16x128_f8f6f4 v[48:51], v[8:15], v[200:207], v[48:51], v181, v181 op_sel_hi:[0,0,0]
	v_mfma_scale_f32_16x16x128_f8f6f4 v[36:39], v[0:7], v[208:215], v[36:39], v181, v181 op_sel_hi:[0,0,0]
	v_mfma_scale_f32_16x16x128_f8f6f4 v[32:35], v[8:15], v[208:215], v[32:35], v181, v181 op_sel_hi:[0,0,0]
	v_mfma_scale_f32_16x16x128_f8f6f4 v[20:23], v[0:7], v[216:223], v[20:23], v181, v181 op_sel_hi:[0,0,0]
	v_mfma_scale_f32_16x16x128_f8f6f4 v[16:19], v[8:15], v[216:223], v[16:19], v181, v181 op_sel_hi:[0,0,0]
	s_setprio 0
	s_setprio 1
	v_mfma_scale_f32_16x16x128_f8f6f4 v[84:87], v[152:159], v[192:199], v[84:87], v181, v181 op_sel_hi:[0,0,0]
	v_mfma_scale_f32_16x16x128_f8f6f4 v[80:83], v[184:191], v[192:199], v[80:83], v181, v181 op_sel_hi:[0,0,0]
	v_mfma_scale_f32_16x16x128_f8f6f4 v[60:63], v[152:159], v[200:207], v[60:63], v181, v181 op_sel_hi:[0,0,0]
	v_mfma_scale_f32_16x16x128_f8f6f4 v[56:59], v[184:191], v[200:207], v[56:59], v181, v181 op_sel_hi:[0,0,0]
	v_mfma_scale_f32_16x16x128_f8f6f4 v[44:47], v[152:159], v[208:215], v[44:47], v181, v181 op_sel_hi:[0,0,0]
	v_mfma_scale_f32_16x16x128_f8f6f4 v[40:43], v[184:191], v[208:215], v[40:43], v181, v181 op_sel_hi:[0,0,0]
	v_mfma_scale_f32_16x16x128_f8f6f4 v[28:31], v[152:159], v[216:223], v[28:31], v181, v181 op_sel_hi:[0,0,0]
	v_mfma_scale_f32_16x16x128_f8f6f4 v[24:27], v[184:191], v[216:223], v[24:27], v181, v181 op_sel_hi:[0,0,0]
	s_setprio 0
	s_barrier
	v_or_b32_e32 v0, 0x18000, v179
	v_add_u32_e32 v1, 0x18400, v179
	ds_read_b128 v[8:11], v0
	ds_read_b128 v[12:15], v1
	v_add_u32_e32 v0, 0x18800, v179
	v_add_u32_e32 v1, 0x18c00, v179
	ds_read_b128 v[152:155], v0
	ds_read_b128 v[156:159], v1
	v_or_b32_e32 v0, 0x19000, v179
	v_add_u32_e32 v4, 0x19400, v179
	v_add_u32_e32 v160, 0x19800, v179
	ds_read_b128 v[0:3], v0
	ds_read_b128 v[4:7], v4
	v_add_u32_e32 v161, 0x19c00, v179
	ds_read_b128 v[184:187], v160
	ds_read_b128 v[188:191], v161
	s_add_u32 s60, s60, 0x40000
	s_addc_u32 s61, s61, 0
	s_mov_b32 m0, s72
	v_lshl_add_u64 v[160:161], s[60:61], 0, v[164:165]
	ds_read_b128 v[192:195], v178 offset:32768
	ds_read_b128 v[196:199], v178 offset:33792
	ds_read_b128 v[200:203], v178 offset:34816
	ds_read_b128 v[204:207], v178 offset:35840
	ds_read_b128 v[208:211], v178 offset:36864
	ds_read_b128 v[212:215], v178 offset:37888
	ds_read_b128 v[216:219], v178 offset:38912
	ds_read_b128 v[220:223], v178 offset:39936
	global_load_lds_dwordx4 v[160:161], off
	v_lshl_add_u64 v[160:161], s[60:61], 0, v[166:167]
	s_mov_b32 m0, s73
	s_nop 0
	global_load_lds_dwordx4 v[160:161], off
	s_waitcnt vmcnt(8)
	s_waitcnt lgkmcnt(0)
	s_barrier
	s_setprio 1
	s_waitcnt lgkmcnt(0)
	v_mfma_scale_f32_16x16x128_f8f6f4 v[132:135], v[8:15], v[192:199], v[132:135], v181, v181 op_sel_hi:[0,0,0]
	v_mfma_scale_f32_16x16x128_f8f6f4 v[128:131], v[152:159], v[192:199], v[128:131], v181, v181 op_sel_hi:[0,0,0]
	v_mfma_scale_f32_16x16x128_f8f6f4 v[116:119], v[8:15], v[200:207], v[116:119], v181, v181 op_sel_hi:[0,0,0]
	v_mfma_scale_f32_16x16x128_f8f6f4 v[112:115], v[152:159], v[200:207], v[112:115], v181, v181 op_sel_hi:[0,0,0]
	v_mfma_scale_f32_16x16x128_f8f6f4 v[100:103], v[8:15], v[208:215], v[100:103], v181, v181 op_sel_hi:[0,0,0]
	v_mfma_scale_f32_16x16x128_f8f6f4 v[96:99], v[152:159], v[208:215], v[96:99], v181, v181 op_sel_hi:[0,0,0]
	v_mfma_scale_f32_16x16x128_f8f6f4 v[76:79], v[8:15], v[216:223], v[76:79], v181, v181 op_sel_hi:[0,0,0]
	v_mfma_scale_f32_16x16x128_f8f6f4 v[72:75], v[152:159], v[216:223], v[72:75], v181, v181 op_sel_hi:[0,0,0]
	s_setprio 0
	s_setprio 1
	v_mfma_scale_f32_16x16x128_f8f6f4 v[140:143], v[0:7], v[192:199], v[140:143], v181, v181 op_sel_hi:[0,0,0]
	v_mfma_scale_f32_16x16x128_f8f6f4 v[136:139], v[184:191], v[192:199], v[136:139], v181, v181 op_sel_hi:[0,0,0]
	v_mfma_scale_f32_16x16x128_f8f6f4 v[124:127], v[0:7], v[200:207], v[124:127], v181, v181 op_sel_hi:[0,0,0]
	v_mfma_scale_f32_16x16x128_f8f6f4 v[120:123], v[184:191], v[200:207], v[120:123], v181, v181 op_sel_hi:[0,0,0]
	v_mfma_scale_f32_16x16x128_f8f6f4 v[108:111], v[0:7], v[208:215], v[108:111], v181, v181 op_sel_hi:[0,0,0]
	v_mfma_scale_f32_16x16x128_f8f6f4 v[104:107], v[184:191], v[208:215], v[104:107], v181, v181 op_sel_hi:[0,0,0]
	v_mfma_scale_f32_16x16x128_f8f6f4 v[92:95], v[0:7], v[216:223], v[92:95], v181, v181 op_sel_hi:[0,0,0]
	v_mfma_scale_f32_16x16x128_f8f6f4 v[88:91], v[184:191], v[216:223], v[88:91], v181, v181 op_sel_hi:[0,0,0]
	s_setprio 0
	s_barrier
	s_mov_b32 m0, s74
	v_lshl_add_u64 v[144:145], v[144:145], 0, s[40:41]
	s_add_u32 s58, s58, 0x40080
	ds_read_b128 v[192:195], v178 offset:49152
	ds_read_b128 v[196:199], v178 offset:50176
	ds_read_b128 v[200:203], v178 offset:51200
	ds_read_b128 v[204:207], v178 offset:52224
	ds_read_b128 v[208:211], v178 offset:53248
	ds_read_b128 v[212:215], v178 offset:54272
	ds_read_b128 v[216:219], v178 offset:55296
	ds_read_b128 v[220:223], v178 offset:56320
	global_load_lds_dwordx4 v[144:145], off
	v_lshl_add_u64 v[144:145], v[146:147], 0, s[40:41]
	s_mov_b32 m0, s75
	s_addc_u32 s59, s59, 0
	global_load_lds_dwordx4 v[144:145], off
	v_lshl_add_u64 v[144:145], s[58:59], 0, v[164:165]
	s_mov_b32 m0, s78
	s_nop 0
	global_load_lds_dwordx4 v[144:145], off
	v_lshl_add_u64 v[144:145], s[58:59], 0, v[166:167]
	s_mov_b32 m0, s79
	s_nop 0
	global_load_lds_dwordx4 v[144:145], off
	v_lshl_add_u64 v[144:145], v[148:149], 0, s[40:41]
	s_mov_b32 m0, s76
	s_nop 0
	global_load_lds_dwordx4 v[144:145], off
	v_lshl_add_u64 v[144:145], v[150:151], 0, s[40:41]
	s_mov_b32 m0, s77
	s_nop 0
	global_load_lds_dwordx4 v[144:145], off
	s_waitcnt vmcnt(8)
	s_waitcnt lgkmcnt(0)
	s_barrier
	s_setprio 1
	s_waitcnt lgkmcnt(0)
	v_mfma_scale_f32_16x16x128_f8f6f4 v[68:71], v[8:15], v[192:199], v[68:71], v181, v181 op_sel_hi:[0,0,0]
	v_mfma_scale_f32_16x16x128_f8f6f4 v[64:67], v[152:159], v[192:199], v[64:67], v181, v181 op_sel_hi:[0,0,0]
	v_mfma_scale_f32_16x16x128_f8f6f4 v[52:55], v[8:15], v[200:207], v[52:55], v181, v181 op_sel_hi:[0,0,0]
	v_mfma_scale_f32_16x16x128_f8f6f4 v[48:51], v[152:159], v[200:207], v[48:51], v181, v181 op_sel_hi:[0,0,0]
	v_mfma_scale_f32_16x16x128_f8f6f4 v[36:39], v[8:15], v[208:215], v[36:39], v181, v181 op_sel_hi:[0,0,0]
	v_mfma_scale_f32_16x16x128_f8f6f4 v[32:35], v[152:159], v[208:215], v[32:35], v181, v181 op_sel_hi:[0,0,0]
	v_mfma_scale_f32_16x16x128_f8f6f4 v[20:23], v[8:15], v[216:223], v[20:23], v181, v181 op_sel_hi:[0,0,0]
	v_mfma_scale_f32_16x16x128_f8f6f4 v[16:19], v[152:159], v[216:223], v[16:19], v181, v181 op_sel_hi:[0,0,0]
	s_setprio 0
	s_setprio 1
	v_mfma_scale_f32_16x16x128_f8f6f4 v[84:87], v[0:7], v[192:199], v[84:87], v181, v181 op_sel_hi:[0,0,0]
	v_mfma_scale_f32_16x16x128_f8f6f4 v[80:83], v[184:191], v[192:199], v[80:83], v181, v181 op_sel_hi:[0,0,0]
	v_mfma_scale_f32_16x16x128_f8f6f4 v[60:63], v[0:7], v[200:207], v[60:63], v181, v181 op_sel_hi:[0,0,0]
	v_mfma_scale_f32_16x16x128_f8f6f4 v[56:59], v[184:191], v[200:207], v[56:59], v181, v181 op_sel_hi:[0,0,0]
	v_mfma_scale_f32_16x16x128_f8f6f4 v[44:47], v[0:7], v[208:215], v[44:47], v181, v181 op_sel_hi:[0,0,0]
	v_mfma_scale_f32_16x16x128_f8f6f4 v[40:43], v[184:191], v[208:215], v[40:43], v181, v181 op_sel_hi:[0,0,0]
	v_mfma_scale_f32_16x16x128_f8f6f4 v[28:31], v[0:7], v[216:223], v[28:31], v181, v181 op_sel_hi:[0,0,0]
	v_mfma_scale_f32_16x16x128_f8f6f4 v[24:27], v[184:191], v[216:223], v[24:27], v181, v181 op_sel_hi:[0,0,0]
	s_setprio 0
	s_barrier
	s_add_i32 s86, s86, 2
	s_add_u32 s10, s10, 0x100
	s_addc_u32 s11, s11, 0
	s_add_u32 s57, s57, 0x100
	s_addc_u32 s85, s85, 0
	s_cmp_gt_u32 s86, 13
	s_cbranch_scc0 .LBB0_384
	s_nop 15
	s_nop 15
	s_nop 15
	s_and_b64 vcc, exec, s[42:43]
	s_cbranch_vccz .LBB0_387
	s_barrier
.LBB0_387:
	v_and_b32_e32 v4, 64, v182
	v_xor_b32_e32 v3, 16, v182
	v_add_u32_e32 v4, 64, v4
	v_cmp_lt_i32_e32 vcc, v3, v4
	s_ashr_i32 s10, s56, 3
	s_ashr_i32 s11, s10, 31
	v_cndmask_b32_e32 v3, v182, v3, vcc
	v_lshlrev_b32_e32 v7, 2, v3
	v_xor_b32_e32 v3, 32, v182
	v_lshl_add_u32 v2, s56, 8, v169
	s_lshl_b64 s[56:57], s[10:11], 25
	v_cmp_lt_i32_e32 vcc, v3, v4
	s_lshl_b32 s10, s36, 2
	s_ashr_i32 s11, s10, 31
	v_cndmask_b32_e32 v3, v182, v3, vcc
	v_lshlrev_b32_e32 v6, 2, v3
	v_ashrrev_i32_e32 v3, 31, v2
	s_add_u32 s56, s62, s56
	v_lshl_or_b32 v0, s36, 8, v180
	v_lshrrev_b32_e32 v144, 4, v182
	v_lshl_add_u32 v0, v144, 2, v0
	v_and_b32_e32 v214, 1, v169
	v_lshl_add_u32 v0, v214, 5, v0
	v_sub_u32_e32 v213, 0, v214
	v_and_b32_e32 v212, 0xfffff000, v213
	s_mov_b32 s100, 0x1000
	s_mov_b32 s101, 0
	s_mov_b32 vcc_lo, 0x55555555
	s_mov_b32 vcc_hi, 0x55555555
	v_lshlrev_b64 v[4:5], 12, v[2:3]
	v_pk_mul_f32 v[8:9], v[134:135], s[46:47] op_sel_hi:[1,0]
	v_pk_mul_f32 v[10:11], v[132:133], s[46:47] op_sel_hi:[1,0]
	s_addc_u32 s57, s63, s57
	v_ashrrev_i32_e32 v1, 31, v0
	v_mul_f32_e32 v12, v11, v11
	v_mul_f32_e32 v13, v9, v9
	v_lshl_add_u64 v[4:5], s[56:57], 0, v[4:5]
	v_fmac_f32_e32 v12, v10, v10
	v_fmac_f32_e32 v13, v8, v8
	v_cvt_pk_bf16_f32 v184, v10, v11
	v_cvt_pk_bf16_f32 v185, v8, v9
	v_lshl_add_u64 v[8:9], v[0:1], 1, v[4:5]
	v_lshl_add_u64 v[8:9], v[8:9], 0, v[212:213]
	v_pk_mul_f32 v[4:5], v[130:131], s[46:47] op_sel_hi:[1,0]
	v_pk_mul_f32 v[10:11], v[128:129], s[46:47] op_sel_hi:[1,0]
	v_add_f32_e32 v12, v12, v13
	v_mul_f32_e32 v13, v11, v11
	v_mul_f32_e32 v14, v5, v5
	v_fmac_f32_e32 v13, v10, v10
	v_fmac_f32_e32 v14, v4, v4
	v_add_f32_e32 v13, v13, v14
	v_add_f32_e32 v128, v12, v13
	v_pk_mul_f32 v[12:13], v[142:143], s[46:47] op_sel_hi:[1,0]
	v_pk_mul_f32 v[14:15], v[140:141], s[46:47] op_sel_hi:[1,0]
	v_cvt_pk_bf16_f32 v186, v10, v11
	v_mul_f32_e32 v11, v15, v15
	v_mul_f32_e32 v129, v13, v13
	v_fmac_f32_e32 v11, v14, v14
	v_fmac_f32_e32 v129, v12, v12
	v_add_f32_e32 v11, v11, v129
	v_add_f32_e32 v11, v128, v11
	v_pk_mul_f32 v[128:129], v[138:139], s[46:47] op_sel_hi:[1,0]
	v_pk_mul_f32 v[130:131], v[136:137], s[46:47] op_sel_hi:[1,0]
	v_mul_f32_e32 v133, v129, v129
	v_mul_f32_e32 v132, v131, v131
	v_fmac_f32_e32 v132, v130, v130
	v_fmac_f32_e32 v133, v128, v128
	v_add_f32_e32 v132, v132, v133
	v_add_f32_e32 v132, v11, v132
	ds_bpermute_b32 v133, v7, v132
	v_cvt_pk_bf16_f32 v187, v4, v5
	s_nop 1
	v_permlane32_swap_b32 v184, v186
	v_permlane32_swap_b32 v185, v187
	s_nop 1
	v_permlane16_swap_b32 v184, v186
	v_permlane16_swap_b32 v185, v187
	v_cvt_pk_bf16_f32 v188, v14, v15
	v_cvt_pk_bf16_f32 v189, v12, v13
	s_waitcnt lgkmcnt(0)
	v_add_f32_e32 v4, v132, v133
	ds_bpermute_b32 v5, v6, v4
	v_cvt_pk_bf16_f32 v190, v130, v131
	v_cvt_pk_bf16_f32 v191, v128, v129
	s_nop 1
	v_permlane32_swap_b32 v188, v190
	v_permlane32_swap_b32 v189, v191
	s_nop 1
	v_permlane16_swap_b32 v188, v190
	v_permlane16_swap_b32 v189, v191
	s_nop 1
	v_cndmask_b32_dpp v200, v188, v184, vcc quad_perm:[0,0,2,2] row_mask:0xf bank_mask:0xf
	v_cndmask_b32_dpp v201, v189, v185, vcc quad_perm:[0,0,2,2] row_mask:0xf bank_mask:0xf
	v_cndmask_b32_dpp v202, v190, v186, vcc quad_perm:[0,0,2,2] row_mask:0xf bank_mask:0xf
	v_cndmask_b32_dpp v203, v191, v187, vcc quad_perm:[0,0,2,2] row_mask:0xf bank_mask:0xf
	s_not_b64 vcc, vcc
	v_cndmask_b32_dpp v188, v184, v188, vcc quad_perm:[1,1,3,3] row_mask:0xf bank_mask:0xf
	v_cndmask_b32_dpp v189, v185, v189, vcc quad_perm:[1,1,3,3] row_mask:0xf bank_mask:0xf
	v_cndmask_b32_dpp v190, v186, v190, vcc quad_perm:[1,1,3,3] row_mask:0xf bank_mask:0xf
	v_cndmask_b32_dpp v191, v187, v191, vcc quad_perm:[1,1,3,3] row_mask:0xf bank_mask:0xf
	s_not_b64 vcc, vcc
	v_lshl_add_u64 v[210:211], v[8:9], 0, s[100:101]
	global_store_dwordx4 v[8:9], v[200:203], off
	global_store_dwordx4 v[210:211], v[188:191], off
	s_nop 1
	s_and_saveexec_b64 s[58:59], s[6:7]
	s_cbranch_execz .LBB0_389
	v_lshlrev_b64 v[8:9], 7, v[2:3]
	v_lshl_add_u64 v[8:9], s[12:13], 0, v[8:9]
	v_lshl_add_u64 v[8:9], s[10:11], 2, v[8:9]
	s_lshl_b32 s36, s5, 2
	v_lshl_add_u64 v[8:9], v[8:9], 0, s[36:37]
	s_waitcnt lgkmcnt(0)
	v_add_f32_e32 v3, v4, v5
	global_store_dword v[8:9], v3, off
.LBB0_389:
	s_or_b64 exec, exec, s[58:59]
	v_or_b32_e32 v4, 16, v2
	s_waitcnt lgkmcnt(0)
	v_ashrrev_i32_e32 v5, 31, v4
	v_lshlrev_b64 v[8:9], 12, v[4:5]
	v_pk_mul_f32 v[10:11], v[118:119], s[46:47] op_sel_hi:[1,0]
	v_pk_mul_f32 v[12:13], v[116:117], s[46:47] op_sel_hi:[1,0]
	v_mul_f32_e32 v14, v11, v11
	v_mul_f32_e32 v3, v13, v13
	v_lshl_add_u64 v[8:9], s[56:57], 0, v[8:9]
	v_fmac_f32_e32 v3, v12, v12
	v_fmac_f32_e32 v14, v10, v10
	v_cvt_pk_bf16_f32 v192, v12, v13
	v_cvt_pk_bf16_f32 v193, v10, v11
	v_lshl_add_u64 v[10:11], v[0:1], 1, v[8:9]
	v_lshl_add_u64 v[10:11], v[10:11], 0, v[212:213]
	v_pk_mul_f32 v[8:9], v[114:115], s[46:47] op_sel_hi:[1,0]
	v_pk_mul_f32 v[12:13], v[112:113], s[46:47] op_sel_hi:[1,0]
	v_add_f32_e32 v3, v3, v14
	v_mul_f32_e32 v14, v13, v13
	v_mul_f32_e32 v15, v9, v9
	v_fmac_f32_e32 v14, v12, v12
	v_fmac_f32_e32 v15, v8, v8
	v_add_f32_e32 v14, v14, v15
	v_add_f32_e32 v3, v3, v14
	v_pk_mul_f32 v[14:15], v[126:127], s[46:47] op_sel_hi:[1,0]
	v_pk_mul_f32 v[112:113], v[124:125], s[46:47] op_sel_hi:[1,0]
	v_cvt_pk_bf16_f32 v194, v12, v13
	v_mul_f32_e32 v13, v113, v113
	v_mul_f32_e32 v114, v15, v15
	v_fmac_f32_e32 v13, v112, v112
	v_fmac_f32_e32 v114, v14, v14
	v_add_f32_e32 v13, v13, v114
	v_pk_mul_f32 v[114:115], v[122:123], s[46:47] op_sel_hi:[1,0]
	v_pk_mul_f32 v[116:117], v[120:121], s[46:47] op_sel_hi:[1,0]
	v_add_f32_e32 v3, v3, v13
	v_mul_f32_e32 v13, v117, v117
	v_mul_f32_e32 v118, v115, v115
	v_fmac_f32_e32 v13, v116, v116
	v_fmac_f32_e32 v118, v114, v114
	v_add_f32_e32 v13, v13, v118
	v_add_f32_e32 v3, v3, v13
	ds_bpermute_b32 v118, v7, v3
	v_cvt_pk_bf16_f32 v195, v8, v9
	s_nop 1
	v_permlane32_swap_b32 v192, v194
	v_permlane32_swap_b32 v193, v195
	s_nop 1
	v_permlane16_swap_b32 v192, v194
	v_permlane16_swap_b32 v193, v195
	v_cvt_pk_bf16_f32 v196, v112, v113
	v_cvt_pk_bf16_f32 v197, v14, v15
	s_waitcnt lgkmcnt(0)
	v_add_f32_e32 v3, v3, v118
	ds_bpermute_b32 v8, v6, v3
	v_cvt_pk_bf16_f32 v198, v116, v117
	v_cvt_pk_bf16_f32 v199, v114, v115
	s_nop 1
	v_permlane32_swap_b32 v196, v198
	v_permlane32_swap_b32 v197, v199
	s_nop 1
	v_permlane16_swap_b32 v196, v198
	v_permlane16_swap_b32 v197, v199
	s_nop 1
	v_cndmask_b32_dpp v204, v196, v192, vcc quad_perm:[0,0,2,2] row_mask:0xf bank_mask:0xf
	v_cndmask_b32_dpp v205, v197, v193, vcc quad_perm:[0,0,2,2] row_mask:0xf bank_mask:0xf
	v_cndmask_b32_dpp v206, v198, v194, vcc quad_perm:[0,0,2,2] row_mask:0xf bank_mask:0xf
	v_cndmask_b32_dpp v207, v199, v195, vcc quad_perm:[0,0,2,2] row_mask:0xf bank_mask:0xf
	s_not_b64 vcc, vcc
	v_cndmask_b32_dpp v196, v192, v196, vcc quad_perm:[1,1,3,3] row_mask:0xf bank_mask:0xf
	v_cndmask_b32_dpp v197, v193, v197, vcc quad_perm:[1,1,3,3] row_mask:0xf bank_mask:0xf
	v_cndmask_b32_dpp v198, v194, v198, vcc quad_perm:[1,1,3,3] row_mask:0xf bank_mask:0xf
	v_cndmask_b32_dpp v199, v195, v199, vcc quad_perm:[1,1,3,3] row_mask:0xf bank_mask:0xf
	s_not_b64 vcc, vcc
	v_lshl_add_u64 v[210:211], v[10:11], 0, s[100:101]
	global_store_dwordx4 v[10:11], v[204:207], off
	global_store_dwordx4 v[210:211], v[196:199], off
	s_nop 1
	s_and_saveexec_b64 s[58:59], s[6:7]
	s_cbranch_execz .LBB0_391
	v_lshlrev_b64 v[4:5], 7, v[4:5]
	v_lshl_add_u64 v[4:5], s[12:13], 0, v[4:5]
	v_lshl_add_u64 v[4:5], s[10:11], 2, v[4:5]
	s_lshl_b32 s36, s5, 2
	v_lshl_add_u64 v[4:5], v[4:5], 0, s[36:37]
	s_waitcnt lgkmcnt(0)
	v_add_f32_e32 v3, v3, v8
	global_store_dword v[4:5], v3, off
.LBB0_391:
	s_or_b64 exec, exec, s[58:59]
	v_or_b32_e32 v4, 32, v2
	v_ashrrev_i32_e32 v5, 31, v4
	s_waitcnt lgkmcnt(0)
	v_lshlrev_b64 v[8:9], 12, v[4:5]
	v_pk_mul_f32 v[10:11], v[102:103], s[46:47] op_sel_hi:[1,0]
	v_pk_mul_f32 v[12:13], v[100:101], s[46:47] op_sel_hi:[1,0]
	v_mul_f32_e32 v14, v11, v11
	v_mul_f32_e32 v3, v13, v13
	v_lshl_add_u64 v[8:9], s[56:57], 0, v[8:9]
	v_fmac_f32_e32 v3, v12, v12
	v_fmac_f32_e32 v14, v10, v10
	v_cvt_pk_bf16_f32 v184, v12, v13
	v_cvt_pk_bf16_f32 v185, v10, v11
	v_lshl_add_u64 v[10:11], v[0:1], 1, v[8:9]
	v_lshl_add_u64 v[10:11], v[10:11], 0, v[212:213]
	v_pk_mul_f32 v[8:9], v[98:99], s[46:47] op_sel_hi:[1,0]
	v_pk_mul_f32 v[12:13], v[96:97], s[46:47] op_sel_hi:[1,0]
	v_add_f32_e32 v3, v3, v14
	v_mul_f32_e32 v14, v13, v13
	v_mul_f32_e32 v15, v9, v9
	v_fmac_f32_e32 v14, v12, v12
	v_fmac_f32_e32 v15, v8, v8
	v_add_f32_e32 v14, v14, v15
	v_add_f32_e32 v3, v3, v14
	v_pk_mul_f32 v[14:15], v[110:111], s[46:47] op_sel_hi:[1,0]
	v_pk_mul_f32 v[96:97], v[108:109], s[46:47] op_sel_hi:[1,0]
	v_cvt_pk_bf16_f32 v186, v12, v13
	v_mul_f32_e32 v13, v97, v97
	v_mul_f32_e32 v98, v15, v15
	v_fmac_f32_e32 v13, v96, v96
	v_fmac_f32_e32 v98, v14, v14
	v_add_f32_e32 v13, v13, v98
	v_pk_mul_f32 v[98:99], v[106:107], s[46:47] op_sel_hi:[1,0]
	v_pk_mul_f32 v[100:101], v[104:105], s[46:47] op_sel_hi:[1,0]
	v_add_f32_e32 v3, v3, v13
	v_mul_f32_e32 v13, v101, v101
	v_mul_f32_e32 v102, v99, v99
	v_fmac_f32_e32 v13, v100, v100
	v_fmac_f32_e32 v102, v98, v98
	v_add_f32_e32 v13, v13, v102
	v_add_f32_e32 v3, v3, v13
	ds_bpermute_b32 v102, v7, v3
	v_cvt_pk_bf16_f32 v187, v8, v9
	s_nop 1
	v_permlane32_swap_b32 v184, v186
	v_permlane32_swap_b32 v185, v187
	s_nop 1
	v_permlane16_swap_b32 v184, v186
	v_permlane16_swap_b32 v185, v187
	v_cvt_pk_bf16_f32 v188, v96, v97
	v_cvt_pk_bf16_f32 v189, v14, v15
	s_waitcnt lgkmcnt(0)
	v_add_f32_e32 v3, v3, v102
	ds_bpermute_b32 v8, v6, v3
	v_cvt_pk_bf16_f32 v190, v100, v101
	v_cvt_pk_bf16_f32 v191, v98, v99
	s_nop 1
	v_permlane32_swap_b32 v188, v190
	v_permlane32_swap_b32 v189, v191
	s_nop 1
	v_permlane16_swap_b32 v188, v190
	v_permlane16_swap_b32 v189, v191
	s_nop 1
	v_cndmask_b32_dpp v200, v188, v184, vcc quad_perm:[0,0,2,2] row_mask:0xf bank_mask:0xf
	v_cndmask_b32_dpp v201, v189, v185, vcc quad_perm:[0,0,2,2] row_mask:0xf bank_mask:0xf
	v_cndmask_b32_dpp v202, v190, v186, vcc quad_perm:[0,0,2,2] row_mask:0xf bank_mask:0xf
	v_cndmask_b32_dpp v203, v191, v187, vcc quad_perm:[0,0,2,2] row_mask:0xf bank_mask:0xf
	s_not_b64 vcc, vcc
	v_cndmask_b32_dpp v188, v184, v188, vcc quad_perm:[1,1,3,3] row_mask:0xf bank_mask:0xf
	v_cndmask_b32_dpp v189, v185, v189, vcc quad_perm:[1,1,3,3] row_mask:0xf bank_mask:0xf
	v_cndmask_b32_dpp v190, v186, v190, vcc quad_perm:[1,1,3,3] row_mask:0xf bank_mask:0xf
	v_cndmask_b32_dpp v191, v187, v191, vcc quad_perm:[1,1,3,3] row_mask:0xf bank_mask:0xf
	s_not_b64 vcc, vcc
	v_lshl_add_u64 v[210:211], v[10:11], 0, s[100:101]
	global_store_dwordx4 v[10:11], v[200:203], off
	global_store_dwordx4 v[210:211], v[188:191], off
	s_nop 1
	s_and_saveexec_b64 s[58:59], s[6:7]
	s_cbranch_execz .LBB0_393
	v_lshlrev_b64 v[4:5], 7, v[4:5]
	v_lshl_add_u64 v[4:5], s[12:13], 0, v[4:5]
	v_lshl_add_u64 v[4:5], s[10:11], 2, v[4:5]
	s_lshl_b32 s36, s5, 2
	v_lshl_add_u64 v[4:5], v[4:5], 0, s[36:37]
	s_waitcnt lgkmcnt(0)
	v_add_f32_e32 v3, v3, v8
	global_store_dword v[4:5], v3, off
.LBB0_393:
	s_or_b64 exec, exec, s[58:59]
	v_or_b32_e32 v4, 48, v2
	v_ashrrev_i32_e32 v5, 31, v4
	s_waitcnt lgkmcnt(0)
	v_lshlrev_b64 v[8:9], 12, v[4:5]
	v_pk_mul_f32 v[10:11], v[78:79], s[46:47] op_sel_hi:[1,0]
	v_pk_mul_f32 v[12:13], v[76:77], s[46:47] op_sel_hi:[1,0]
	v_mul_f32_e32 v14, v11, v11
	v_mul_f32_e32 v3, v13, v13
	v_lshl_add_u64 v[8:9], s[56:57], 0, v[8:9]
	v_fmac_f32_e32 v3, v12, v12
	v_fmac_f32_e32 v14, v10, v10
	v_cvt_pk_bf16_f32 v192, v12, v13
	v_cvt_pk_bf16_f32 v193, v10, v11
	v_lshl_add_u64 v[10:11], v[0:1], 1, v[8:9]
	v_lshl_add_u64 v[10:11], v[10:11], 0, v[212:213]
	v_pk_mul_f32 v[8:9], v[74:75], s[46:47] op_sel_hi:[1,0]
	v_pk_mul_f32 v[12:13], v[72:73], s[46:47] op_sel_hi:[1,0]
	v_add_f32_e32 v3, v3, v14
	v_mul_f32_e32 v14, v13, v13
	v_mul_f32_e32 v15, v9, v9
	v_fmac_f32_e32 v14, v12, v12
	v_fmac_f32_e32 v15, v8, v8
	v_add_f32_e32 v14, v14, v15
	v_add_f32_e32 v3, v3, v14
	v_pk_mul_f32 v[14:15], v[94:95], s[46:47] op_sel_hi:[1,0]
	v_pk_mul_f32 v[72:73], v[92:93], s[46:47] op_sel_hi:[1,0]
	v_cvt_pk_bf16_f32 v194, v12, v13
	v_mul_f32_e32 v13, v73, v73
	v_mul_f32_e32 v74, v15, v15
	v_fmac_f32_e32 v13, v72, v72
	v_fmac_f32_e32 v74, v14, v14
	v_add_f32_e32 v13, v13, v74
	v_pk_mul_f32 v[74:75], v[90:91], s[46:47] op_sel_hi:[1,0]
	v_pk_mul_f32 v[76:77], v[88:89], s[46:47] op_sel_hi:[1,0]
	v_add_f32_e32 v3, v3, v13
	v_mul_f32_e32 v13, v77, v77
	v_mul_f32_e32 v78, v75, v75
	v_fmac_f32_e32 v13, v76, v76
	v_fmac_f32_e32 v78, v74, v74
	v_add_f32_e32 v13, v13, v78
	v_add_f32_e32 v3, v3, v13
	ds_bpermute_b32 v78, v7, v3
	v_cvt_pk_bf16_f32 v195, v8, v9
	s_nop 1
	v_permlane32_swap_b32 v192, v194
	v_permlane32_swap_b32 v193, v195
	s_nop 1
	v_permlane16_swap_b32 v192, v194
	v_permlane16_swap_b32 v193, v195
	v_cvt_pk_bf16_f32 v196, v72, v73
	v_cvt_pk_bf16_f32 v197, v14, v15
	s_waitcnt lgkmcnt(0)
	v_add_f32_e32 v3, v3, v78
	ds_bpermute_b32 v8, v6, v3
	v_cvt_pk_bf16_f32 v198, v76, v77
	v_cvt_pk_bf16_f32 v199, v74, v75
	s_nop 1
	v_permlane32_swap_b32 v196, v198
	v_permlane32_swap_b32 v197, v199
	s_nop 1
	v_permlane16_swap_b32 v196, v198
	v_permlane16_swap_b32 v197, v199
	s_nop 1
	v_cndmask_b32_dpp v204, v196, v192, vcc quad_perm:[0,0,2,2] row_mask:0xf bank_mask:0xf
	v_cndmask_b32_dpp v205, v197, v193, vcc quad_perm:[0,0,2,2] row_mask:0xf bank_mask:0xf
	v_cndmask_b32_dpp v206, v198, v194, vcc quad_perm:[0,0,2,2] row_mask:0xf bank_mask:0xf
	v_cndmask_b32_dpp v207, v199, v195, vcc quad_perm:[0,0,2,2] row_mask:0xf bank_mask:0xf
	s_not_b64 vcc, vcc
	v_cndmask_b32_dpp v196, v192, v196, vcc quad_perm:[1,1,3,3] row_mask:0xf bank_mask:0xf
	v_cndmask_b32_dpp v197, v193, v197, vcc quad_perm:[1,1,3,3] row_mask:0xf bank_mask:0xf
	v_cndmask_b32_dpp v198, v194, v198, vcc quad_perm:[1,1,3,3] row_mask:0xf bank_mask:0xf
	v_cndmask_b32_dpp v199, v195, v199, vcc quad_perm:[1,1,3,3] row_mask:0xf bank_mask:0xf
	s_not_b64 vcc, vcc
	v_lshl_add_u64 v[210:211], v[10:11], 0, s[100:101]
	global_store_dwordx4 v[10:11], v[204:207], off
	global_store_dwordx4 v[210:211], v[196:199], off
	s_nop 1
	s_and_saveexec_b64 s[58:59], s[6:7]
	s_cbranch_execz .LBB0_395
	v_lshlrev_b64 v[4:5], 7, v[4:5]
	v_lshl_add_u64 v[4:5], s[12:13], 0, v[4:5]
	v_lshl_add_u64 v[4:5], s[10:11], 2, v[4:5]
	s_lshl_b32 s36, s5, 2
	v_lshl_add_u64 v[4:5], v[4:5], 0, s[36:37]
	s_waitcnt lgkmcnt(0)
	v_add_f32_e32 v3, v3, v8
	global_store_dword v[4:5], v3, off
.LBB0_395:
	s_or_b64 exec, exec, s[58:59]
	v_add_u32_e32 v4, 0x80, v2
	v_ashrrev_i32_e32 v5, 31, v4
	s_waitcnt lgkmcnt(0)
	v_lshlrev_b64 v[8:9], 12, v[4:5]
	v_pk_mul_f32 v[10:11], v[70:71], s[46:47] op_sel_hi:[1,0]
	v_pk_mul_f32 v[12:13], v[68:69], s[46:47] op_sel_hi:[1,0]
	v_mul_f32_e32 v14, v11, v11
	v_mul_f32_e32 v3, v13, v13
	v_lshl_add_u64 v[8:9], s[56:57], 0, v[8:9]
	v_fmac_f32_e32 v3, v12, v12
	v_fmac_f32_e32 v14, v10, v10
	v_cvt_pk_bf16_f32 v184, v12, v13
	v_cvt_pk_bf16_f32 v185, v10, v11
	v_lshl_add_u64 v[10:11], v[0:1], 1, v[8:9]
	v_lshl_add_u64 v[10:11], v[10:11], 0, v[212:213]
	v_pk_mul_f32 v[8:9], v[66:67], s[46:47] op_sel_hi:[1,0]
	v_pk_mul_f32 v[12:13], v[64:65], s[46:47] op_sel_hi:[1,0]
	v_add_f32_e32 v3, v3, v14
	v_mul_f32_e32 v14, v13, v13
	v_mul_f32_e32 v15, v9, v9
	v_fmac_f32_e32 v14, v12, v12
	v_fmac_f32_e32 v15, v8, v8
	v_add_f32_e32 v14, v14, v15
	v_add_f32_e32 v3, v3, v14
	v_pk_mul_f32 v[14:15], v[86:87], s[46:47] op_sel_hi:[1,0]
	v_pk_mul_f32 v[64:65], v[84:85], s[46:47] op_sel_hi:[1,0]
	v_cvt_pk_bf16_f32 v186, v12, v13
	v_mul_f32_e32 v13, v65, v65
	v_mul_f32_e32 v66, v15, v15
	v_fmac_f32_e32 v13, v64, v64
	v_fmac_f32_e32 v66, v14, v14
	v_add_f32_e32 v13, v13, v66
	v_pk_mul_f32 v[66:67], v[82:83], s[46:47] op_sel_hi:[1,0]
	v_pk_mul_f32 v[68:69], v[80:81], s[46:47] op_sel_hi:[1,0]
	v_add_f32_e32 v3, v3, v13
	v_mul_f32_e32 v13, v69, v69
	v_mul_f32_e32 v70, v67, v67
	v_fmac_f32_e32 v13, v68, v68
	v_fmac_f32_e32 v70, v66, v66
	v_add_f32_e32 v13, v13, v70
	v_add_f32_e32 v3, v3, v13
	ds_bpermute_b32 v70, v7, v3
	v_cvt_pk_bf16_f32 v187, v8, v9
	s_nop 1
	v_permlane32_swap_b32 v184, v186
	v_permlane32_swap_b32 v185, v187
	s_nop 1
	v_permlane16_swap_b32 v184, v186
	v_permlane16_swap_b32 v185, v187
	v_cvt_pk_bf16_f32 v188, v64, v65
	v_cvt_pk_bf16_f32 v189, v14, v15
	s_waitcnt lgkmcnt(0)
	v_add_f32_e32 v3, v3, v70
	ds_bpermute_b32 v8, v6, v3
	v_cvt_pk_bf16_f32 v190, v68, v69
	v_cvt_pk_bf16_f32 v191, v66, v67
	s_nop 1
	v_permlane32_swap_b32 v188, v190
	v_permlane32_swap_b32 v189, v191
	s_nop 1
	v_permlane16_swap_b32 v188, v190
	v_permlane16_swap_b32 v189, v191
	s_nop 1
	v_cndmask_b32_dpp v200, v188, v184, vcc quad_perm:[0,0,2,2] row_mask:0xf bank_mask:0xf
	v_cndmask_b32_dpp v201, v189, v185, vcc quad_perm:[0,0,2,2] row_mask:0xf bank_mask:0xf
	v_cndmask_b32_dpp v202, v190, v186, vcc quad_perm:[0,0,2,2] row_mask:0xf bank_mask:0xf
	v_cndmask_b32_dpp v203, v191, v187, vcc quad_perm:[0,0,2,2] row_mask:0xf bank_mask:0xf
	s_not_b64 vcc, vcc
	v_cndmask_b32_dpp v188, v184, v188, vcc quad_perm:[1,1,3,3] row_mask:0xf bank_mask:0xf
	v_cndmask_b32_dpp v189, v185, v189, vcc quad_perm:[1,1,3,3] row_mask:0xf bank_mask:0xf
	v_cndmask_b32_dpp v190, v186, v190, vcc quad_perm:[1,1,3,3] row_mask:0xf bank_mask:0xf
	v_cndmask_b32_dpp v191, v187, v191, vcc quad_perm:[1,1,3,3] row_mask:0xf bank_mask:0xf
	s_not_b64 vcc, vcc
	v_lshl_add_u64 v[210:211], v[10:11], 0, s[100:101]
	global_store_dwordx4 v[10:11], v[200:203], off
	global_store_dwordx4 v[210:211], v[188:191], off
	s_nop 1
	s_and_saveexec_b64 s[58:59], s[6:7]
	s_cbranch_execz .LBB0_397
	v_lshlrev_b64 v[4:5], 7, v[4:5]
	v_lshl_add_u64 v[4:5], s[12:13], 0, v[4:5]
	v_lshl_add_u64 v[4:5], s[10:11], 2, v[4:5]
	s_lshl_b32 s36, s5, 2
	v_lshl_add_u64 v[4:5], v[4:5], 0, s[36:37]
	s_waitcnt lgkmcnt(0)
	v_add_f32_e32 v3, v3, v8
	global_store_dword v[4:5], v3, off
.LBB0_397:
	s_or_b64 exec, exec, s[58:59]
	v_add_u32_e32 v4, 0x90, v2
	v_ashrrev_i32_e32 v5, 31, v4
	s_waitcnt lgkmcnt(0)
	v_lshlrev_b64 v[8:9], 12, v[4:5]
	v_pk_mul_f32 v[10:11], v[54:55], s[46:47] op_sel_hi:[1,0]
	v_pk_mul_f32 v[12:13], v[52:53], s[46:47] op_sel_hi:[1,0]
	v_mul_f32_e32 v14, v11, v11
	v_mul_f32_e32 v3, v13, v13
	v_lshl_add_u64 v[8:9], s[56:57], 0, v[8:9]
	v_fmac_f32_e32 v3, v12, v12
	v_fmac_f32_e32 v14, v10, v10
	v_cvt_pk_bf16_f32 v192, v12, v13
	v_cvt_pk_bf16_f32 v193, v10, v11
	v_lshl_add_u64 v[10:11], v[0:1], 1, v[8:9]
	v_lshl_add_u64 v[10:11], v[10:11], 0, v[212:213]
	v_pk_mul_f32 v[8:9], v[50:51], s[46:47] op_sel_hi:[1,0]
	v_pk_mul_f32 v[12:13], v[48:49], s[46:47] op_sel_hi:[1,0]
	v_add_f32_e32 v3, v3, v14
	v_mul_f32_e32 v14, v13, v13
	v_mul_f32_e32 v15, v9, v9
	v_fmac_f32_e32 v14, v12, v12
	v_fmac_f32_e32 v15, v8, v8
	v_add_f32_e32 v14, v14, v15
	v_add_f32_e32 v3, v3, v14
	v_pk_mul_f32 v[14:15], v[62:63], s[46:47] op_sel_hi:[1,0]
	v_pk_mul_f32 v[48:49], v[60:61], s[46:47] op_sel_hi:[1,0]
	v_cvt_pk_bf16_f32 v194, v12, v13
	v_mul_f32_e32 v13, v49, v49
	v_mul_f32_e32 v50, v15, v15
	v_fmac_f32_e32 v13, v48, v48
	v_fmac_f32_e32 v50, v14, v14
	v_add_f32_e32 v13, v13, v50
	v_pk_mul_f32 v[50:51], v[58:59], s[46:47] op_sel_hi:[1,0]
	v_pk_mul_f32 v[52:53], v[56:57], s[46:47] op_sel_hi:[1,0]
	v_add_f32_e32 v3, v3, v13
	v_mul_f32_e32 v13, v53, v53
	v_mul_f32_e32 v54, v51, v51
	v_fmac_f32_e32 v13, v52, v52
	v_fmac_f32_e32 v54, v50, v50
	v_add_f32_e32 v13, v13, v54
	v_add_f32_e32 v3, v3, v13
	ds_bpermute_b32 v54, v7, v3
	v_cvt_pk_bf16_f32 v195, v8, v9
	s_nop 1
	v_permlane32_swap_b32 v192, v194
	v_permlane32_swap_b32 v193, v195
	s_nop 1
	v_permlane16_swap_b32 v192, v194
	v_permlane16_swap_b32 v193, v195
	v_cvt_pk_bf16_f32 v196, v48, v49
	v_cvt_pk_bf16_f32 v197, v14, v15
	s_waitcnt lgkmcnt(0)
	v_add_f32_e32 v3, v3, v54
	ds_bpermute_b32 v8, v6, v3
	v_cvt_pk_bf16_f32 v198, v52, v53
	v_cvt_pk_bf16_f32 v199, v50, v51
	s_nop 1
	v_permlane32_swap_b32 v196, v198
	v_permlane32_swap_b32 v197, v199
	s_nop 1
	v_permlane16_swap_b32 v196, v198
	v_permlane16_swap_b32 v197, v199
	s_nop 1
	v_cndmask_b32_dpp v204, v196, v192, vcc quad_perm:[0,0,2,2] row_mask:0xf bank_mask:0xf
	v_cndmask_b32_dpp v205, v197, v193, vcc quad_perm:[0,0,2,2] row_mask:0xf bank_mask:0xf
	v_cndmask_b32_dpp v206, v198, v194, vcc quad_perm:[0,0,2,2] row_mask:0xf bank_mask:0xf
	v_cndmask_b32_dpp v207, v199, v195, vcc quad_perm:[0,0,2,2] row_mask:0xf bank_mask:0xf
	s_not_b64 vcc, vcc
	v_cndmask_b32_dpp v196, v192, v196, vcc quad_perm:[1,1,3,3] row_mask:0xf bank_mask:0xf
	v_cndmask_b32_dpp v197, v193, v197, vcc quad_perm:[1,1,3,3] row_mask:0xf bank_mask:0xf
	v_cndmask_b32_dpp v198, v194, v198, vcc quad_perm:[1,1,3,3] row_mask:0xf bank_mask:0xf
	v_cndmask_b32_dpp v199, v195, v199, vcc quad_perm:[1,1,3,3] row_mask:0xf bank_mask:0xf
	s_not_b64 vcc, vcc
	v_lshl_add_u64 v[210:211], v[10:11], 0, s[100:101]
	global_store_dwordx4 v[10:11], v[204:207], off
	global_store_dwordx4 v[210:211], v[196:199], off
	s_nop 1
	s_and_saveexec_b64 s[58:59], s[6:7]
	s_cbranch_execz .LBB0_399
	v_lshlrev_b64 v[4:5], 7, v[4:5]
	v_lshl_add_u64 v[4:5], s[12:13], 0, v[4:5]
	v_lshl_add_u64 v[4:5], s[10:11], 2, v[4:5]
	s_lshl_b32 s36, s5, 2
	v_lshl_add_u64 v[4:5], v[4:5], 0, s[36:37]
	s_waitcnt lgkmcnt(0)
	v_add_f32_e32 v3, v3, v8
	global_store_dword v[4:5], v3, off
.LBB0_399:
	s_or_b64 exec, exec, s[58:59]
	v_add_u32_e32 v4, 0xa0, v2
	v_ashrrev_i32_e32 v5, 31, v4
	s_waitcnt lgkmcnt(0)
	v_lshlrev_b64 v[8:9], 12, v[4:5]
	v_pk_mul_f32 v[10:11], v[38:39], s[46:47] op_sel_hi:[1,0]
	v_pk_mul_f32 v[12:13], v[36:37], s[46:47] op_sel_hi:[1,0]
	v_mul_f32_e32 v14, v11, v11
	v_mul_f32_e32 v3, v13, v13
	v_lshl_add_u64 v[8:9], s[56:57], 0, v[8:9]
	v_fmac_f32_e32 v3, v12, v12
	v_fmac_f32_e32 v14, v10, v10
	v_cvt_pk_bf16_f32 v184, v12, v13
	v_cvt_pk_bf16_f32 v185, v10, v11
	v_lshl_add_u64 v[10:11], v[0:1], 1, v[8:9]
	v_lshl_add_u64 v[10:11], v[10:11], 0, v[212:213]
	v_pk_mul_f32 v[8:9], v[34:35], s[46:47] op_sel_hi:[1,0]
	v_pk_mul_f32 v[12:13], v[32:33], s[46:47] op_sel_hi:[1,0]
	v_add_f32_e32 v3, v3, v14
	v_mul_f32_e32 v14, v13, v13
	v_mul_f32_e32 v15, v9, v9
	v_fmac_f32_e32 v14, v12, v12
	v_fmac_f32_e32 v15, v8, v8
	v_add_f32_e32 v14, v14, v15
	v_add_f32_e32 v3, v3, v14
	v_pk_mul_f32 v[14:15], v[46:47], s[46:47] op_sel_hi:[1,0]
	v_pk_mul_f32 v[32:33], v[44:45], s[46:47] op_sel_hi:[1,0]
	v_cvt_pk_bf16_f32 v186, v12, v13
	v_mul_f32_e32 v13, v33, v33
	v_mul_f32_e32 v34, v15, v15
	v_fmac_f32_e32 v13, v32, v32
	v_fmac_f32_e32 v34, v14, v14
	v_add_f32_e32 v13, v13, v34
	v_pk_mul_f32 v[34:35], v[42:43], s[46:47] op_sel_hi:[1,0]
	v_pk_mul_f32 v[36:37], v[40:41], s[46:47] op_sel_hi:[1,0]
	v_add_f32_e32 v3, v3, v13
	v_mul_f32_e32 v13, v37, v37
	v_mul_f32_e32 v38, v35, v35
	v_fmac_f32_e32 v13, v36, v36
	v_fmac_f32_e32 v38, v34, v34
	v_add_f32_e32 v13, v13, v38
	v_add_f32_e32 v3, v3, v13
	ds_bpermute_b32 v38, v7, v3
	v_cvt_pk_bf16_f32 v187, v8, v9
	s_nop 1
	v_permlane32_swap_b32 v184, v186
	v_permlane32_swap_b32 v185, v187
	s_nop 1
	v_permlane16_swap_b32 v184, v186
	v_permlane16_swap_b32 v185, v187
	v_cvt_pk_bf16_f32 v188, v32, v33
	v_cvt_pk_bf16_f32 v189, v14, v15
	s_waitcnt lgkmcnt(0)
	v_add_f32_e32 v3, v3, v38
	ds_bpermute_b32 v8, v6, v3
	v_cvt_pk_bf16_f32 v190, v36, v37
	v_cvt_pk_bf16_f32 v191, v34, v35
	s_nop 1
	v_permlane32_swap_b32 v188, v190
	v_permlane32_swap_b32 v189, v191
	s_nop 1
	v_permlane16_swap_b32 v188, v190
	v_permlane16_swap_b32 v189, v191
	s_nop 1
	v_cndmask_b32_dpp v200, v188, v184, vcc quad_perm:[0,0,2,2] row_mask:0xf bank_mask:0xf
	v_cndmask_b32_dpp v201, v189, v185, vcc quad_perm:[0,0,2,2] row_mask:0xf bank_mask:0xf
	v_cndmask_b32_dpp v202, v190, v186, vcc quad_perm:[0,0,2,2] row_mask:0xf bank_mask:0xf
	v_cndmask_b32_dpp v203, v191, v187, vcc quad_perm:[0,0,2,2] row_mask:0xf bank_mask:0xf
	s_not_b64 vcc, vcc
	v_cndmask_b32_dpp v188, v184, v188, vcc quad_perm:[1,1,3,3] row_mask:0xf bank_mask:0xf
	v_cndmask_b32_dpp v189, v185, v189, vcc quad_perm:[1,1,3,3] row_mask:0xf bank_mask:0xf
	v_cndmask_b32_dpp v190, v186, v190, vcc quad_perm:[1,1,3,3] row_mask:0xf bank_mask:0xf
	v_cndmask_b32_dpp v191, v187, v191, vcc quad_perm:[1,1,3,3] row_mask:0xf bank_mask:0xf
	s_not_b64 vcc, vcc
	v_lshl_add_u64 v[210:211], v[10:11], 0, s[100:101]
	global_store_dwordx4 v[10:11], v[200:203], off
	global_store_dwordx4 v[210:211], v[188:191], off
	s_nop 1
	s_and_saveexec_b64 s[58:59], s[6:7]
	s_cbranch_execz .LBB0_401
	v_lshlrev_b64 v[4:5], 7, v[4:5]
	v_lshl_add_u64 v[4:5], s[12:13], 0, v[4:5]
	v_lshl_add_u64 v[4:5], s[10:11], 2, v[4:5]
	s_lshl_b32 s36, s5, 2
	v_lshl_add_u64 v[4:5], v[4:5], 0, s[36:37]
	s_waitcnt lgkmcnt(0)
	v_add_f32_e32 v3, v3, v8
	global_store_dword v[4:5], v3, off
.LBB0_401:
	s_or_b64 exec, exec, s[58:59]
	v_add_u32_e32 v2, 0xb0, v2
	v_ashrrev_i32_e32 v3, 31, v2
	v_lshlrev_b64 v[4:5], 12, v[2:3]
	s_waitcnt lgkmcnt(0)
	v_pk_mul_f32 v[8:9], v[22:23], s[46:47] op_sel_hi:[1,0]
	v_pk_mul_f32 v[10:11], v[20:21], s[46:47] op_sel_hi:[1,0]
	v_mul_f32_e32 v13, v9, v9
	v_mul_f32_e32 v12, v11, v11
	v_lshl_add_u64 v[4:5], s[56:57], 0, v[4:5]
	v_fmac_f32_e32 v12, v10, v10
	v_fmac_f32_e32 v13, v8, v8
	v_cvt_pk_bf16_f32 v192, v10, v11
	v_cvt_pk_bf16_f32 v193, v8, v9
	v_lshl_add_u64 v[4:5], v[0:1], 1, v[4:5]
	v_lshl_add_u64 v[4:5], v[4:5], 0, v[212:213]
	v_pk_mul_f32 v[0:1], v[18:19], s[46:47] op_sel_hi:[1,0]
	v_pk_mul_f32 v[8:9], v[16:17], s[46:47] op_sel_hi:[1,0]
	v_mul_f32_e32 v10, v9, v9
	v_mul_f32_e32 v11, v1, v1
	v_fmac_f32_e32 v10, v8, v8
	v_fmac_f32_e32 v11, v0, v0
	v_add_f32_e32 v12, v12, v13
	v_add_f32_e32 v10, v10, v11
	v_add_f32_e32 v14, v12, v10
	v_pk_mul_f32 v[10:11], v[30:31], s[46:47] op_sel_hi:[1,0]
	v_pk_mul_f32 v[12:13], v[28:29], s[46:47] op_sel_hi:[1,0]
	v_cvt_pk_bf16_f32 v194, v8, v9
	v_mul_f32_e32 v9, v13, v13
	v_mul_f32_e32 v15, v11, v11
	v_fmac_f32_e32 v9, v12, v12
	v_fmac_f32_e32 v15, v10, v10
	v_add_f32_e32 v9, v9, v15
	v_add_f32_e32 v9, v14, v9
	v_pk_mul_f32 v[14:15], v[26:27], s[46:47] op_sel_hi:[1,0]
	v_pk_mul_f32 v[16:17], v[24:25], s[46:47] op_sel_hi:[1,0]
	v_mul_f32_e32 v19, v15, v15
	v_mul_f32_e32 v18, v17, v17
	v_fmac_f32_e32 v18, v16, v16
	v_fmac_f32_e32 v19, v14, v14
	v_add_f32_e32 v18, v18, v19
	v_add_f32_e32 v18, v9, v18
	ds_bpermute_b32 v7, v7, v18
	v_cvt_pk_bf16_f32 v195, v0, v1
	s_nop 1
	v_permlane32_swap_b32 v192, v194
	v_permlane32_swap_b32 v193, v195
	s_nop 1
	v_permlane16_swap_b32 v192, v194
	v_permlane16_swap_b32 v193, v195
	v_cvt_pk_bf16_f32 v196, v12, v13
	v_cvt_pk_bf16_f32 v197, v10, v11
	s_waitcnt lgkmcnt(0)
	v_add_f32_e32 v0, v18, v7
	ds_bpermute_b32 v1, v6, v0
	v_cvt_pk_bf16_f32 v198, v16, v17
	v_cvt_pk_bf16_f32 v199, v14, v15
	s_nop 1
	v_permlane32_swap_b32 v196, v198
	v_permlane32_swap_b32 v197, v199
	s_nop 1
	v_permlane16_swap_b32 v196, v198
	v_permlane16_swap_b32 v197, v199
	s_nop 1
	v_cndmask_b32_dpp v204, v196, v192, vcc quad_perm:[0,0,2,2] row_mask:0xf bank_mask:0xf
	v_cndmask_b32_dpp v205, v197, v193, vcc quad_perm:[0,0,2,2] row_mask:0xf bank_mask:0xf
	v_cndmask_b32_dpp v206, v198, v194, vcc quad_perm:[0,0,2,2] row_mask:0xf bank_mask:0xf
	v_cndmask_b32_dpp v207, v199, v195, vcc quad_perm:[0,0,2,2] row_mask:0xf bank_mask:0xf
	s_not_b64 vcc, vcc
	v_cndmask_b32_dpp v196, v192, v196, vcc quad_perm:[1,1,3,3] row_mask:0xf bank_mask:0xf
	v_cndmask_b32_dpp v197, v193, v197, vcc quad_perm:[1,1,3,3] row_mask:0xf bank_mask:0xf
	v_cndmask_b32_dpp v198, v194, v198, vcc quad_perm:[1,1,3,3] row_mask:0xf bank_mask:0xf
	v_cndmask_b32_dpp v199, v195, v199, vcc quad_perm:[1,1,3,3] row_mask:0xf bank_mask:0xf
	s_not_b64 vcc, vcc
	v_lshl_add_u64 v[210:211], v[4:5], 0, s[100:101]
	global_store_dwordx4 v[4:5], v[204:207], off
	global_store_dwordx4 v[210:211], v[196:199], off
	s_nop 1
	s_and_saveexec_b64 s[56:57], s[6:7]
	s_cbranch_execz .LBB0_403
	v_lshlrev_b64 v[2:3], 7, v[2:3]
	v_lshl_add_u64 v[2:3], s[12:13], 0, v[2:3]
	v_lshl_add_u64 v[2:3], s[10:11], 2, v[2:3]
	s_lshl_b32 s36, s5, 2
	v_lshl_add_u64 v[2:3], v[2:3], 0, s[36:37]
	s_waitcnt lgkmcnt(0)
	v_add_f32_e32 v0, v0, v1
	global_store_dword v[2:3], v0, off
.LBB0_403:
	s_or_b64 exec, exec, s[56:57]
	s_and_b64 vcc, exec, s[8:9]
	s_mov_b64 s[8:9], -1
	s_cbranch_vccnz .LBB0_374
	v_lshl_add_u32 v0, s50, 8, v169
	v_lshl_or_b32 v2, s48, 8, v180
	s_waitcnt lgkmcnt(0)
	v_ashrrev_i32_e32 v1, 31, v0
	v_ashrrev_i32_e32 v3, 31, v2
	v_lshlrev_b64 v[4:5], 13, v[0:1]
	v_lshl_add_u64 v[4:5], s[16:17], 0, v[4:5]
	v_lshlrev_b64 v[2:3], 2, v[2:3]
	v_lshl_add_u64 v[100:101], v[4:5], 0, v[2:3]
	v_or_b32_e32 v4, 16, v0
	v_ashrrev_i32_e32 v5, 31, v4
	v_lshlrev_b64 v[4:5], 13, v[4:5]
	v_lshl_add_u64 v[4:5], s[16:17], 0, v[4:5]
	v_lshl_add_u64 v[4:5], v[4:5], 0, v[2:3]
	global_load_dwordx4 v[72:75], v[100:101], off nt
	global_load_dwordx4 v[68:71], v[100:101], off offset:64 nt
	global_load_dwordx4 v[20:23], v[100:101], off offset:128 nt
	global_load_dwordx4 v[16:19], v[100:101], off offset:192 nt
	global_load_dwordx4 v[88:91], v[4:5], off nt
	global_load_dwordx4 v[76:79], v[4:5], off offset:64 nt
	global_load_dwordx4 v[36:39], v[4:5], off offset:128 nt
	global_load_dwordx4 v[32:35], v[4:5], off offset:192 nt
	v_or_b32_e32 v4, 32, v0
	v_or_b32_e32 v0, 48, v0
	v_ashrrev_i32_e32 v5, 31, v4
	v_ashrrev_i32_e32 v1, 31, v0
	v_lshlrev_b64 v[4:5], 13, v[4:5]
	v_lshlrev_b64 v[0:1], 13, v[0:1]
	v_lshl_add_u64 v[4:5], s[16:17], 0, v[4:5]
	v_lshl_add_u64 v[0:1], s[16:17], 0, v[0:1]
	v_lshl_add_u64 v[4:5], v[4:5], 0, v[2:3]
	v_lshl_add_u64 v[0:1], v[0:1], 0, v[2:3]
	v_add_co_u32_e32 v2, vcc, s47, v100
	global_load_dwordx4 v[96:99], v[4:5], off nt
	global_load_dwordx4 v[92:95], v[4:5], off offset:64 nt
	global_load_dwordx4 v[44:47], v[4:5], off offset:128 nt
	global_load_dwordx4 v[40:43], v[4:5], off offset:192 nt
	v_addc_co_u32_e32 v3, vcc, 0, v101, vcc
	v_add_co_u32_e32 v10, vcc, s65, v100
	global_load_dwordx4 v[108:111], v[0:1], off nt
	global_load_dwordx4 v[104:107], v[0:1], off offset:64 nt
	global_load_dwordx4 v[56:59], v[0:1], off offset:128 nt
	global_load_dwordx4 v[48:51], v[0:1], off offset:192 nt
	v_addc_co_u32_e32 v11, vcc, 0, v101, vcc
	v_add_co_u32_e32 v26, vcc, s66, v100
	v_lshl_add_u64 v[0:1], v[100:101], 0, s[18:19]
	s_nop 0
	v_addc_co_u32_e32 v27, vcc, 0, v101, vcc
	v_lshl_add_u64 v[8:9], v[100:101], 0, s[20:21]
	v_lshl_add_u64 v[24:25], v[100:101], 0, s[26:27]
	v_lshl_add_u64 v[102:103], v[100:101], 0, s[28:29]
	v_add_co_u32_e32 v100, vcc, 0x160000, v100
	global_load_dwordx4 v[52:55], v[0:1], off offset:64 nt
	global_load_dwordx4 v[4:7], v[0:1], off offset:128 nt
	global_load_dwordx4 v[64:67], v[2:3], off nt
	s_nop 0
	global_load_dwordx4 v[0:3], v[0:1], off offset:192 nt
	s_nop 0
	global_load_dwordx4 v[60:63], v[8:9], off offset:64 nt
	global_load_dwordx4 v[12:15], v[8:9], off offset:128 nt
	global_load_dwordx4 v[84:87], v[10:11], off nt
	s_nop 0
	global_load_dwordx4 v[8:11], v[8:9], off offset:192 nt
	s_nop 0
	global_load_dwordx4 v[80:83], v[24:25], off offset:64 nt
	global_load_dwordx4 v[28:31], v[24:25], off offset:128 nt
	global_load_dwordx4 v[156:159], v[26:27], off nt
	s_nop 0
	global_load_dwordx4 v[24:27], v[24:25], off offset:192 nt
	v_addc_co_u32_e32 v101, vcc, 0, v101, vcc
	global_load_dwordx4 v[152:155], v[102:103], off offset:64 nt
	global_load_dwordx4 v[148:151], v[102:103], off offset:128 nt
	global_load_dwordx4 v[160:163], v[100:101], off nt
	global_load_dwordx4 v[144:147], v[102:103], off offset:192 nt
	s_andn2_b64 vcc, exec, s[38:39]
	s_cbranch_vccnz .LBB0_373
	s_barrier
	s_branch .LBB0_373
